# global barrier: L1 invalidate issued after the leader election (overlaps the leader's L2 write-back instead of delaying the election)
# baseline (speedup 1.0000x reference)
; DI void grid_barrier(unsigned* bar, unsigned gen) {
;   asm volatile("s_waitcnt vmcnt(0)" ::: "memory");
;   __syncthreads();
;   if (threadIdx.x == 0) {
;     __builtin_amdgcn_fence(__ATOMIC_RELEASE, "agent");
;     const unsigned grp = blockIdx.x & 15u;
;     const unsigned nblk = (gridDim.x + 15u - grp) >> 4;
;     unsigned old = __hip_atomic_fetch_add(bar + 64 * (1 + grp), 1u, __ATOMIC_RELAXED, __HIP_MEMORY_SCOPE_AGENT);
;     if (old + 1u == nblk * gen) {
;       unsigned g = __hip_atomic_fetch_add(bar, 1u, __ATOMIC_RELAXED, __HIP_MEMORY_SCOPE_AGENT);
;       if (g + 1u == 16u * gen) {
;         for (int i = 0; i < 16; ++i) __hip_atomic_store(bar + 64 * (17 + i), gen, __ATOMIC_RELAXED, __HIP_MEMORY_SCOPE_AGENT);
;       }
;     }
;     while (__hip_atomic_load(bar + 64 * (17 + grp), __ATOMIC_RELAXED, __HIP_MEMORY_SCOPE_AGENT) < gen) __builtin_amdgcn_s_sleep(4);
;     __builtin_amdgcn_fence(__ATOMIC_ACQUIRE, "agent");
;   }
.Lmy_xb_glob:
	v_mov_b32_e32 v0, s17
	v_add_u32_e32 v0, 0x1400, v0
	global_atomic_add v3, v0, v2, s[12:13] sc0
	s_waitcnt vmcnt(0)
	v_readfirstlane_b32 s18, v3
	s_add_i32 s18, s18, 1
	s_mul_i32 s19, s20, s15
	s_cmp_eq_u32 s18, s19
	buffer_inv sc1
	s_cbranch_scc0 .Lmy_xb_follow
	buffer_wbl2 sc1
	s_waitcnt vmcnt(0)
	v_mov_b32_e32 v0, 0x3400
	global_atomic_add v0, v2, s[12:13]
	s_mul_i32 s19, s20, s16
